# one static s_setprio 1 for waves 0-3 at kernel entry (mirror of the previous variant)
# speedup vs baseline: 1.0121x; 1.0121x over previous
_Z4mega6Params:
	v_readfirstlane_b32 s4, v0
	s_nop 3
	s_bfe_u32 s4, s4, 0x40006
	s_cmp_lt_u32 s4, 4
	s_cbranch_scc0 .Lprio_done
	s_setprio 1
